# attention unit ends no longer drain their output stores before the barrier; NA prologue waits only for its LDS writes
# speedup vs baseline: 1.0061x; 1.0016x over previous
; template <int MODE>
; __device__ __forceinline__ void attn_unit(unsigned char* ws_, const float* rpb, const float* sink, int l, int h, int qb, int kvq, unsigned char* lds_g) {
;     ...
;   if (MODE == 0) { Qp = proj + C_QA + 128 * h; Kp = proj + C_KA + 128 * h; Vp = proj + C_VA + 128 * h; ldq = ldk = ldv = DINP; ycol = 128 * h; C = 0.08838834764831845f * LOG2E; }
;   else if (MODE == 1) { Qp = (const bf16_t*)(ws_ + WS_Q) + 192 * h; Kp = (const bf16_t*)(ws_ + WS_K) + 192 * h; Vp = (const bf16_t*)(ws_ + WS_V) + 128 * h; ldq = QLD; ldk = KLD; ldv = VLD; ycol = 512 + 128 * h; C = 0.07216878364870322f * LOG2E; }
;   else { Qp = proj + C_QC + 128 * h; Kp = proj + C_KC + 128 * (h / 3); Vp = proj + C_VC + 128 * (h / 3); ldq = ldk = ldv = DINP; ycol = 1280 + 128 * h; C = 0.08838834764831845f * LOG2E; }
;   const int q0 = qb * 256, qi = q0 + wid * 32 + r32;
;   int T0, T1, tw0, tw1, wrow = 0, qcol = 0, c0 = 0; float slope2 = 0.f;
;   if (MODE == 1) { T0 = tw0 = kvq * (S / 64 / KVSPLIT); T1 = tw1 = T0 + S / 64 / KVSPLIT; }
;   else if (MODE == 0) { const int R = qb * 4; T0 = min(max(R - 4, 0), 120); T1 = min(max(R - 1, 0), 120) + 8; wrow = R + (wid >> 1); tw0 = min(max(wrow - 4, 0), 120); tw1 = tw0 + 8;
;                         qcol = (wid & 1) * 32 + r32; c0 = min(max(qcol - 8, 0), 48); }
;   else { T0 = max(0, (q0 - 128) >> 6); T1 = min(S / 64, ((q0 + 255 + 128) >> 6) + 1); const int qw = q0 + wid * 32; tw0 = max(0, (qw - 128) >> 6); tw1 = min(S / 64, ((qw + 31 + 128) >> 6) + 1);
;          slope2 = exp2f(-8.0f * (float)(h + 1) / 6.0f) * LOG2E; }
;   LAS float* wsl = (LAS float*)(ldl + OFF_WS) + wid * 64; LAS float* li_l = wsl; LAS float* al_l = wsl + 32;
;   LAS float* rpbL = (LAS float*)(ldl + OFF_RPB);
;   if (MODE == 0) { for (int i = tid; i < 465; i += NTHREADS) rpbL[i] = rpb[(l * 4 + h) * 465 + i] * LOG2E; }
;   float m_reg = -1e29f, l_reg = 0.f;
;   if (MODE == 2) { m_reg = sink[l * 6 + h] * LOG2E; l_reg = hi == 0 ? 1.f : 0.f; }
;   f32x16 o[4] = {}; bf16x8 qr[ND];
;   { const bf16_t* Qw = Qp + (size_t)qi * ldq + hi * 8;
; #pragma unroll
;     for (int d0 = 0; d0 < ND; ++d0) qr[d0] = *(const bf16x8*)(Qw + d0 * 16); }
;   unsigned kg[NCH], vg[2];
; #pragma unroll
;   for (int i = 0; i < NCH; ++i) { const int X = (wid + 8 * i) * 1024 + lane * 16, row = X / (DQK * 2), cs = X % (DQK * 2), colB = cs ^ kswz_x<DQK>(row); kg[i] = (unsigned)(row * ldk + (colB >> 1)) * 2u; }
.LBB0_688:
	s_or_b64 exec, exec, s[2:3]
	s_lshl_b32 s90, s6, 7
	s_and_b32 s42, s30, 31
	s_lshl_b64 s[92:93], s[90:91], 1
	s_add_u32 s2, s94, s92
	s_addc_u32 s4, s95, s93
	s_add_u32 s0, s2, 0x11828000
	s_addc_u32 s1, s4, 0
	s_add_u32 s5, s2, 0x11828400
	s_addc_u32 s6, s4, 0
	v_ashrrev_i32_e32 v5, 6, v8
	s_add_u32 s3, s2, 0x11828800
	s_addc_u32 s4, s4, 0
	v_lshlrev_b32_e32 v15, 5, v5
	s_lshl_b32 s2, s42, 2
	v_and_b32_e32 v159, 31, v8
	v_lshl_add_u32 v144, s42, 8, v15
	v_sub_u32_e64 v2, s2, 1 clamp
	v_bfe_u32 v158, v8, 5, 1
	v_or_b32_e32 v0, v144, v159
	v_readfirstlane_b32 s7, v2
	v_mov_b64_e32 v[2:3], s[0:1]
	s_movk_i32 s0, 0x1e00
	v_mad_i64_i32 v[2:3], s[0:1], v0, s0, v[2:3]
	v_lshlrev_b32_e32 v146, 4, v158
	v_mov_b32_e32 v147, v1
	v_and_b32_e32 v145, 63, v8
	v_lshl_add_u64 v[2:3], v[2:3], 0, v[146:147]
	flat_load_dwordx4 v[112:115], v[2:3]
	flat_load_dwordx4 v[116:119], v[2:3] offset:32
	flat_load_dwordx4 v[120:123], v[2:3] offset:64
	flat_load_dwordx4 v[124:127], v[2:3] offset:96
	flat_load_dwordx4 v[128:131], v[2:3] offset:128
	flat_load_dwordx4 v[132:135], v[2:3] offset:160
	flat_load_dwordx4 v[136:139], v[2:3] offset:192
	flat_load_dwordx4 v[140:143], v[2:3] offset:224
	v_lshlrev_b32_e32 v3, 10, v5
	v_lshlrev_b32_e32 v16, 4, v145
	v_or_b32_e32 v2, v3, v16
	v_bfe_i32 v0, v5, 21, 1
	v_add_u32_sdwa v0, v2, v0 dst_sel:DWORD dst_unused:UNUSED_PAD src0_sel:DWORD src1_sel:BYTE_3
	v_ashrrev_i32_e32 v0, 8, v0
	v_and_b32_e32 v6, 7, v0
	v_lshrrev_b32_e32 v9, 1, v0
	v_mul_i32_i24_e32 v4, 0x100, v0
	v_and_or_b32 v6, v9, 8, v6
	v_sub_u32_e32 v4, v2, v4
	v_lshlrev_b32_e32 v6, 4, v6
	v_mul_i32_i24_e32 v0, 0x1e00, v0
	v_add_u32_e32 v2, 0x2000, v2
	v_xad_u32 v0, v6, v4, v0
	v_ashrrev_i32_e32 v4, 31, v2
	v_add_u32_sdwa v4, v2, v4 dst_sel:DWORD dst_unused:UNUSED_PAD src0_sel:DWORD src1_sel:BYTE_3
	v_ashrrev_i32_e32 v4, 8, v4
	v_mul_i32_i24_e32 v6, 0x100, v4
	v_sub_u32_e32 v2, v2, v6
	v_and_b32_e32 v6, 7, v4
	v_lshrrev_b32_e32 v9, 1, v4
	v_and_or_b32 v6, v9, 8, v6
	v_ashrrev_i32_e32 v14, 8, v3
	v_add_u32_e32 v3, 0x2000, v3
	v_lshlrev_b32_e32 v6, 4, v6
	v_mul_i32_i24_e32 v4, 0x1e00, v4
	v_bfe_u32 v11, v8, 2, 3
	s_mov_b32 s0, 0xfffff8
	v_ashrrev_i32_e32 v13, 8, v3
	v_sub_u32_e64 v7, s2, 4 clamp
	v_xad_u32 v2, v6, v2, v4
	v_and_or_b32 v4, v14, s0, v11
	v_and_or_b32 v3, v13, s0, v11
	v_readfirstlane_b32 s0, v5
	s_lshl_b32 s8, s0, 10
	v_readfirstlane_b32 s0, v7
	s_min_u32 s59, s7, 0x78
	s_mul_i32 s0, s0, 0x3c000
	s_max_u32 s43, s2, 4
	s_add_i32 s59, s59, 8
	s_lshl_b32 s7, s0, 1
	s_add_u32 s0, s5, s7
	v_lshlrev_b32_e32 v17, 3, v145
	s_addc_u32 s1, s6, 0
	s_add_i32 s60, s8, 0
	v_and_b32_e32 v9, 32, v8
	v_and_b32_e32 v12, 64, v8
	v_and_b32_e32 v10, 24, v17
	s_add_i32 m0, s60, 0xc000
	v_or3_b32 v6, v10, v9, v12
	v_mul_u32_u24_e32 v4, 0xf00, v4
	s_waitcnt lgkmcnt(0)
	s_barrier
	global_load_lds_dwordx4 v0, s[0:1]
	s_add_i32 m0, s60, 0xe000
	v_or_b32_e32 v4, v4, v6
	v_mul_u32_u24_e32 v3, 0xf00, v3
	global_load_lds_dwordx4 v2, s[0:1]
	s_add_u32 s0, s3, s7
	v_lshlrev_b32_e32 v4, 1, v4
	v_or_b32_e32 v3, v3, v6
	s_addc_u32 s1, s4, 0
	s_mov_b32 m0, s60
	v_lshlrev_b32_e32 v6, 1, v3
	global_load_lds_dwordx4 v4, s[0:1]
	s_add_i32 m0, s60, 0x2000
	v_readfirstlane_b32 s61, v7
	global_load_lds_dwordx4 v6, s[0:1]
	s_add_i32 s0, s43, -3
	s_cmp_ge_u32 s0, s59
	s_mov_b64 s[0:1], -1
	s_cbranch_scc0 .LBB0_690
	s_waitcnt vmcnt(0)
	s_mov_b64 s[0:1], 0

; __device__ __forceinline__ int crow(int r, int hi) { return (r & 3) + 8 * (r >> 2) + 4 * hi; }
; __device__ __forceinline__ unsigned cvtpk(float lo, float hi) { unsigned r; asm volatile("v_cvt_pk_bf16_f32 %0, %1, %2" : "=v"(r) : "v"(lo), "v"(hi)); return r; }
; template <int MODE>
; __device__ __forceinline__ void attn_unit(unsigned char* ws_, const float* rpb, const float* sink, int l, int h, int qb, int kvq, unsigned char* lds_g) {
;     ...
;   { auto rr = __builtin_amdgcn_permlane32_swap(__float_as_uint(l_reg), __float_as_uint(l_reg), false, false); l_reg = __uint_as_float(rr[0]) + __uint_as_float(rr[1]); }
;   if (hi == 0) li_l[r32] = l_reg; asm volatile("s_waitcnt lgkmcnt(0)" ::: "memory");
;   bf16_t* Ow; int ldo;
;   if (MODE == 1) { Ow = (bf16_t*)(ws_ + WS_PART) + ((size_t)kvq * S + q0 + wid * 32) * VLD + 128 * h + r32; ldo = VLD;
;     if (hi == 0) { float* st = (float*)(ws_ + WS_STAT) + ((size_t)(kvq * 6 + h) * S + qi) * 2; st[0] = m_reg; st[1] = l_reg; } }
;   else { Ow = (bf16_t*)(ws_ + WS_Y) + (size_t)(q0 + wid * 32) * DM + ycol + r32; ldo = DM; }
; #pragma unroll
;   for (int r = 0; r < 16; ++r) { const int orow = crow(r, hi); const float rl = __builtin_amdgcn_rcpf(li_l[orow]);
; #pragma unroll
;     for (int d0 = 0; d0 < 4; ++d0) Ow[(size_t)orow * ldo + d0 * 32] = (bf16_t)(cvtpk(o[d0][r] * rl, 0.f) & 0xffffu); }
.LBB0_774:
	v_mov_b32_e32 v0, v174
	s_nop 1
	v_permlane32_swap_b32_e32 v174, v0
	v_cmp_gt_u32_e32 vcc, 32, v145
	s_and_saveexec_b64 s[0:1], vcc
	v_add_f32_e32 v0, v174, v0
	v_lshl_add_u32 v2, v159, 2, v147
	ds_write_b32 v2, v0
	s_or_b64 exec, exec, s[0:1]
	s_waitcnt lgkmcnt(0)
	v_lshl_add_u32 v6, v158, 4, v147
	ds_read_b32 v4, v6
	v_ashrrev_i32_e32 v145, 31, v144
	v_lshlrev_b64 v[2:3], 12, v[144:145]
	v_lshl_add_u64 v[2:3], s[94:95], 0, v[2:3]
	v_lshl_add_u64 v[2:3], s[90:91], 1, v[2:3]
	s_waitcnt lgkmcnt(0)
	v_rcp_f32_e32 v7, v4
	v_lshlrev_b32_e32 v0, 1, v159
	v_lshl_add_u64 v[2:3], v[2:3], 0, v[0:1]
	s_mov_b64 s[0:1], 0x18628000
	v_lshl_add_u64 v[2:3], v[2:3], 0, s[0:1]
	v_lshlrev_b32_e32 v0, 14, v158
	v_mul_f32_e32 v8, v64, v7
	v_lshl_add_u64 v[4:5], v[2:3], 0, v[0:1]
	v_cvt_pk_bf16_f32 v8, v8, v1
	flat_store_short v[4:5], v8
	v_mul_f32_e32 v8, v48, v7
	v_cvt_pk_bf16_f32 v8, v8, v1
	flat_store_short v[4:5], v8 offset:64
	v_mul_f32_e32 v8, v32, v7
	v_cvt_pk_bf16_f32 v8, v8, v1
	v_mul_f32_e32 v7, v16, v7
	flat_store_short v[4:5], v8 offset:128
	v_cvt_pk_bf16_f32 v7, v7, v1
	ds_read_b32 v8, v6 offset:4
	flat_store_short v[4:5], v7 offset:192
	v_or_b32_e32 v4, 0x1000, v0
	v_mov_b32_e32 v5, v1
	v_lshl_add_u64 v[4:5], v[2:3], 0, v[4:5]
	s_waitcnt lgkmcnt(0)
	v_rcp_f32_e32 v7, v8
	s_nop 0
	v_mul_f32_e32 v8, v65, v7
	v_cvt_pk_bf16_f32 v8, v8, v1
	flat_store_short v[4:5], v8
	v_mul_f32_e32 v8, v49, v7
	v_cvt_pk_bf16_f32 v8, v8, v1
	flat_store_short v[4:5], v8 offset:64
	v_mul_f32_e32 v8, v33, v7
	v_cvt_pk_bf16_f32 v8, v8, v1
	v_mul_f32_e32 v7, v17, v7
	flat_store_short v[4:5], v8 offset:128
	v_cvt_pk_bf16_f32 v7, v7, v1
	ds_read_b32 v8, v6 offset:8
	flat_store_short v[4:5], v7 offset:192
	v_or_b32_e32 v4, 0x2000, v0
	v_mov_b32_e32 v5, v1
	v_lshl_add_u64 v[4:5], v[2:3], 0, v[4:5]
	s_waitcnt lgkmcnt(0)
	v_rcp_f32_e32 v7, v8
	s_nop 0
	v_mul_f32_e32 v8, v66, v7
	v_cvt_pk_bf16_f32 v8, v8, v1
	flat_store_short v[4:5], v8
	v_mul_f32_e32 v8, v50, v7
	v_cvt_pk_bf16_f32 v8, v8, v1
	flat_store_short v[4:5], v8 offset:64
	v_mul_f32_e32 v8, v34, v7
	v_cvt_pk_bf16_f32 v8, v8, v1
	v_mul_f32_e32 v7, v18, v7
	flat_store_short v[4:5], v8 offset:128
	v_cvt_pk_bf16_f32 v7, v7, v1
	ds_read_b32 v8, v6 offset:12
	flat_store_short v[4:5], v7 offset:192
	v_or_b32_e32 v4, 0x3000, v0
	v_mov_b32_e32 v5, v1
	v_lshl_add_u64 v[4:5], v[2:3], 0, v[4:5]
	s_waitcnt lgkmcnt(0)
	v_rcp_f32_e32 v7, v8
	s_nop 0
	v_mul_f32_e32 v8, v67, v7
	v_cvt_pk_bf16_f32 v8, v8, v1
	flat_store_short v[4:5], v8
	v_mul_f32_e32 v8, v51, v7
	v_cvt_pk_bf16_f32 v8, v8, v1
	flat_store_short v[4:5], v8 offset:64
	v_mul_f32_e32 v8, v35, v7
	v_cvt_pk_bf16_f32 v8, v8, v1
	v_mul_f32_e32 v7, v19, v7
	flat_store_short v[4:5], v8 offset:128
	v_cvt_pk_bf16_f32 v7, v7, v1
	ds_read_b32 v8, v6 offset:32
	flat_store_short v[4:5], v7 offset:192
	v_or_b32_e32 v4, 0x8000, v0
	v_mov_b32_e32 v5, v1
	v_lshl_add_u64 v[4:5], v[2:3], 0, v[4:5]
	s_waitcnt lgkmcnt(0)
	v_rcp_f32_e32 v7, v8
	s_nop 0
	v_mul_f32_e32 v8, v68, v7
	v_cvt_pk_bf16_f32 v8, v8, v1
	flat_store_short v[4:5], v8
	v_mul_f32_e32 v8, v52, v7
	v_cvt_pk_bf16_f32 v8, v8, v1
	flat_store_short v[4:5], v8 offset:64
	v_mul_f32_e32 v8, v36, v7
	v_cvt_pk_bf16_f32 v8, v8, v1
	v_mul_f32_e32 v7, v20, v7
	flat_store_short v[4:5], v8 offset:128
	v_cvt_pk_bf16_f32 v7, v7, v1
	ds_read_b32 v8, v6 offset:36
	flat_store_short v[4:5], v7 offset:192
	v_or_b32_e32 v4, 0x9000, v0
	v_mov_b32_e32 v5, v1
	v_lshl_add_u64 v[4:5], v[2:3], 0, v[4:5]
	s_waitcnt lgkmcnt(0)
	v_rcp_f32_e32 v7, v8
	s_nop 0
	v_mul_f32_e32 v8, v69, v7
	v_cvt_pk_bf16_f32 v8, v8, v1
	flat_store_short v[4:5], v8
	v_mul_f32_e32 v8, v53, v7
	v_cvt_pk_bf16_f32 v8, v8, v1
	flat_store_short v[4:5], v8 offset:64
	v_mul_f32_e32 v8, v37, v7
	v_cvt_pk_bf16_f32 v8, v8, v1
	v_mul_f32_e32 v7, v21, v7
	flat_store_short v[4:5], v8 offset:128
	v_cvt_pk_bf16_f32 v7, v7, v1
	ds_read_b32 v8, v6 offset:40
	flat_store_short v[4:5], v7 offset:192
	v_or_b32_e32 v4, 0xa000, v0
	v_mov_b32_e32 v5, v1
	v_lshl_add_u64 v[4:5], v[2:3], 0, v[4:5]
	s_waitcnt lgkmcnt(0)
	v_rcp_f32_e32 v7, v8
	s_nop 0
	v_mul_f32_e32 v8, v70, v7
	v_cvt_pk_bf16_f32 v8, v8, v1
	flat_store_short v[4:5], v8
	v_mul_f32_e32 v8, v54, v7
	v_cvt_pk_bf16_f32 v8, v8, v1
	flat_store_short v[4:5], v8 offset:64
	v_mul_f32_e32 v8, v38, v7
	v_cvt_pk_bf16_f32 v8, v8, v1
	v_mul_f32_e32 v7, v22, v7
	flat_store_short v[4:5], v8 offset:128
	v_cvt_pk_bf16_f32 v7, v7, v1
	ds_read_b32 v8, v6 offset:44
	flat_store_short v[4:5], v7 offset:192
	v_or_b32_e32 v4, 0xb000, v0
	v_mov_b32_e32 v5, v1
	v_lshl_add_u64 v[4:5], v[2:3], 0, v[4:5]
	s_waitcnt lgkmcnt(0)
; __device__ __forceinline__ int crow(int r, int hi) { return (r & 3) + 8 * (r >> 2) + 4 * hi; }
; __device__ __forceinline__ unsigned cvtpk(float lo, float hi) { unsigned r; asm volatile("v_cvt_pk_bf16_f32 %0, %1, %2" : "=v"(r) : "v"(lo), "v"(hi)); return r; }
; template <int MODE>
; __device__ __forceinline__ void attn_unit(unsigned char* ws_, const float* rpb, const float* sink, int l, int h, int qb, int kvq, unsigned char* lds_g) {
;     ...
;   for (int r = 0; r < 16; ++r) { const int orow = crow(r, hi); const float rl = __builtin_amdgcn_rcpf(li_l[orow]);
; #pragma unroll
;     for (int d0 = 0; d0 < 4; ++d0) Ow[(size_t)orow * ldo + d0 * 32] = (bf16_t)(cvtpk(o[d0][r] * rl, 0.f) & 0xffffu); }
;   asm volatile("s_waitcnt lgkmcnt(0)" ::: "memory");
;   __syncthreads();
	v_rcp_f32_e32 v7, v8
	s_nop 0
	v_mul_f32_e32 v8, v71, v7
	v_cvt_pk_bf16_f32 v8, v8, v1
	flat_store_short v[4:5], v8
	v_mul_f32_e32 v8, v55, v7
	v_cvt_pk_bf16_f32 v8, v8, v1
	flat_store_short v[4:5], v8 offset:64
	v_mul_f32_e32 v8, v39, v7
	v_cvt_pk_bf16_f32 v8, v8, v1
	v_mul_f32_e32 v7, v23, v7
	flat_store_short v[4:5], v8 offset:128
	v_cvt_pk_bf16_f32 v7, v7, v1
	ds_read_b32 v8, v6 offset:64
	flat_store_short v[4:5], v7 offset:192
	v_or_b32_e32 v4, 0x10000, v0
	v_mov_b32_e32 v5, v1
	v_lshl_add_u64 v[4:5], v[2:3], 0, v[4:5]
	s_waitcnt lgkmcnt(0)
	v_rcp_f32_e32 v7, v8
	s_nop 0
	v_mul_f32_e32 v8, v72, v7
	v_cvt_pk_bf16_f32 v8, v8, v1
	flat_store_short v[4:5], v8
	v_mul_f32_e32 v8, v56, v7
	v_cvt_pk_bf16_f32 v8, v8, v1
	flat_store_short v[4:5], v8 offset:64
	v_mul_f32_e32 v8, v40, v7
	v_cvt_pk_bf16_f32 v8, v8, v1
	v_mul_f32_e32 v7, v24, v7
	flat_store_short v[4:5], v8 offset:128
	v_cvt_pk_bf16_f32 v7, v7, v1
	ds_read_b32 v8, v6 offset:68
	flat_store_short v[4:5], v7 offset:192
	v_or_b32_e32 v4, 0x11000, v0
	v_mov_b32_e32 v5, v1
	v_lshl_add_u64 v[4:5], v[2:3], 0, v[4:5]
	s_waitcnt lgkmcnt(0)
	v_rcp_f32_e32 v7, v8
	s_nop 0
	v_mul_f32_e32 v8, v73, v7
	v_cvt_pk_bf16_f32 v8, v8, v1
	flat_store_short v[4:5], v8
	v_mul_f32_e32 v8, v57, v7
	v_cvt_pk_bf16_f32 v8, v8, v1
	flat_store_short v[4:5], v8 offset:64
	v_mul_f32_e32 v8, v41, v7
	v_cvt_pk_bf16_f32 v8, v8, v1
	v_mul_f32_e32 v7, v25, v7
	flat_store_short v[4:5], v8 offset:128
	v_cvt_pk_bf16_f32 v7, v7, v1
	ds_read_b32 v8, v6 offset:72
	flat_store_short v[4:5], v7 offset:192
	v_or_b32_e32 v4, 0x12000, v0
	v_mov_b32_e32 v5, v1
	v_lshl_add_u64 v[4:5], v[2:3], 0, v[4:5]
	s_waitcnt lgkmcnt(0)
	v_rcp_f32_e32 v7, v8
	s_nop 0
	v_mul_f32_e32 v8, v74, v7
	v_cvt_pk_bf16_f32 v8, v8, v1
	flat_store_short v[4:5], v8
	v_mul_f32_e32 v8, v58, v7
	v_cvt_pk_bf16_f32 v8, v8, v1
	flat_store_short v[4:5], v8 offset:64
	v_mul_f32_e32 v8, v42, v7
	v_cvt_pk_bf16_f32 v8, v8, v1
	v_mul_f32_e32 v7, v26, v7
	flat_store_short v[4:5], v8 offset:128
	v_cvt_pk_bf16_f32 v7, v7, v1
	ds_read_b32 v8, v6 offset:76
	flat_store_short v[4:5], v7 offset:192
	v_or_b32_e32 v4, 0x13000, v0
	v_mov_b32_e32 v5, v1
	v_lshl_add_u64 v[4:5], v[2:3], 0, v[4:5]
	s_waitcnt lgkmcnt(0)
	v_rcp_f32_e32 v7, v8
	s_nop 0
	v_mul_f32_e32 v8, v75, v7
	v_cvt_pk_bf16_f32 v8, v8, v1
	flat_store_short v[4:5], v8
	v_mul_f32_e32 v8, v59, v7
	v_cvt_pk_bf16_f32 v8, v8, v1
	flat_store_short v[4:5], v8 offset:64
	v_mul_f32_e32 v8, v43, v7
	v_cvt_pk_bf16_f32 v8, v8, v1
	v_mul_f32_e32 v7, v27, v7
	flat_store_short v[4:5], v8 offset:128
	v_cvt_pk_bf16_f32 v7, v7, v1
	ds_read_b32 v8, v6 offset:96
	flat_store_short v[4:5], v7 offset:192
	v_or_b32_e32 v4, 0x18000, v0
	v_mov_b32_e32 v5, v1
	v_lshl_add_u64 v[4:5], v[2:3], 0, v[4:5]
	s_waitcnt lgkmcnt(0)
	v_rcp_f32_e32 v7, v8
	s_nop 0
	v_mul_f32_e32 v8, v76, v7
	v_cvt_pk_bf16_f32 v8, v8, v1
	flat_store_short v[4:5], v8
	v_mul_f32_e32 v8, v60, v7
	v_cvt_pk_bf16_f32 v8, v8, v1
	flat_store_short v[4:5], v8 offset:64
	v_mul_f32_e32 v8, v44, v7
	v_cvt_pk_bf16_f32 v8, v8, v1
	v_mul_f32_e32 v7, v28, v7
	flat_store_short v[4:5], v8 offset:128
	v_cvt_pk_bf16_f32 v7, v7, v1
	ds_read_b32 v8, v6 offset:100
	flat_store_short v[4:5], v7 offset:192
	v_or_b32_e32 v4, 0x19000, v0
	v_mov_b32_e32 v5, v1
	v_lshl_add_u64 v[4:5], v[2:3], 0, v[4:5]
	s_waitcnt lgkmcnt(0)
	v_rcp_f32_e32 v7, v8
	s_nop 0
	v_mul_f32_e32 v8, v77, v7
	v_cvt_pk_bf16_f32 v8, v8, v1
	flat_store_short v[4:5], v8
	v_mul_f32_e32 v8, v61, v7
	v_cvt_pk_bf16_f32 v8, v8, v1
	flat_store_short v[4:5], v8 offset:64
	v_mul_f32_e32 v8, v45, v7
	v_cvt_pk_bf16_f32 v8, v8, v1
	v_mul_f32_e32 v7, v29, v7
	flat_store_short v[4:5], v8 offset:128
	v_cvt_pk_bf16_f32 v7, v7, v1
	ds_read_b32 v8, v6 offset:104
	flat_store_short v[4:5], v7 offset:192
	v_or_b32_e32 v4, 0x1a000, v0
	v_mov_b32_e32 v5, v1
	v_lshl_add_u64 v[4:5], v[2:3], 0, v[4:5]
	s_waitcnt lgkmcnt(0)
	v_rcp_f32_e32 v7, v8
	v_or_b32_e32 v0, 0x1b000, v0
	v_lshl_add_u64 v[2:3], v[2:3], 0, v[0:1]
	v_mul_f32_e32 v8, v78, v7
	v_cvt_pk_bf16_f32 v8, v8, v1
	flat_store_short v[4:5], v8
	v_mul_f32_e32 v8, v62, v7
	v_cvt_pk_bf16_f32 v8, v8, v1
	flat_store_short v[4:5], v8 offset:64
	v_mul_f32_e32 v8, v46, v7
	v_mul_f32_e32 v7, v30, v7
	v_cvt_pk_bf16_f32 v8, v8, v1
	flat_store_short v[4:5], v8 offset:128
	v_cvt_pk_bf16_f32 v7, v7, v1
	ds_read_b32 v6, v6 offset:108
	flat_store_short v[4:5], v7 offset:192
	s_waitcnt lgkmcnt(0)
	v_rcp_f32_e32 v6, v6
	s_nop 0
	v_mul_f32_e32 v0, v79, v6
	v_cvt_pk_bf16_f32 v0, v0, v1
	flat_store_short v[2:3], v0
	v_mul_f32_e32 v0, v63, v6
	v_cvt_pk_bf16_f32 v0, v0, v1
	flat_store_short v[2:3], v0 offset:64
	v_mul_f32_e32 v0, v47, v6
	v_cvt_pk_bf16_f32 v0, v0, v1
	flat_store_short v[2:3], v0 offset:128
	v_mul_f32_e32 v0, v31, v6
	v_cvt_pk_bf16_f32 v0, v0, v1
	flat_store_short v[2:3], v0 offset:192
	s_waitcnt lgkmcnt(0)
	s_barrier

; __device__ __forceinline__ int crow(int r, int hi) { return (r & 3) + 8 * (r >> 2) + 4 * hi; }
; __device__ __forceinline__ unsigned cvtpk(float lo, float hi) { unsigned r; asm volatile("v_cvt_pk_bf16_f32 %0, %1, %2" : "=v"(r) : "v"(lo), "v"(hi)); return r; }
; template <int MODE>
; __device__ __forceinline__ void attn_unit(unsigned char* ws_, const float* rpb, const float* sink, int l, int h, int qb, int kvq, unsigned char* lds_g) {
;     ...
;   { auto rr = __builtin_amdgcn_permlane32_swap(__float_as_uint(l_reg), __float_as_uint(l_reg), false, false); l_reg = __uint_as_float(rr[0]) + __uint_as_float(rr[1]); }
;   if (hi == 0) li_l[r32] = l_reg; asm volatile("s_waitcnt lgkmcnt(0)" ::: "memory");
;   bf16_t* Ow; int ldo;
;   if (MODE == 1) { Ow = (bf16_t*)(ws_ + WS_PART) + ((size_t)kvq * S + q0 + wid * 32) * VLD + 128 * h + r32; ldo = VLD;
;     if (hi == 0) { float* st = (float*)(ws_ + WS_STAT) + ((size_t)(kvq * 6 + h) * S + qi) * 2; st[0] = m_reg; st[1] = l_reg; } }
;   else { Ow = (bf16_t*)(ws_ + WS_Y) + (size_t)(q0 + wid * 32) * DM + ycol + r32; ldo = DM; }
; #pragma unroll
;   for (int r = 0; r < 16; ++r) { const int orow = crow(r, hi); const float rl = __builtin_amdgcn_rcpf(li_l[orow]);
; #pragma unroll
;     for (int d0 = 0; d0 < 4; ++d0) Ow[(size_t)orow * ldo + d0 * 32] = (bf16_t)(cvtpk(o[d0][r] * rl, 0.f) & 0xffffu); }
.LBB0_778:
	s_or_b64 exec, exec, s[0:1]
	s_waitcnt lgkmcnt(0)
	v_lshl_add_u32 v6, v198, 4, v200
	ds_read_b32 v4, v6
	v_ashrrev_i32_e32 v177, 31, v176
	v_lshlrev_b64 v[2:3], 12, v[176:177]
	v_lshl_add_u64 v[2:3], s[8:9], 0, v[2:3]
	s_lshl_b32 s90, s2, 1
	s_waitcnt lgkmcnt(0)
	v_rcp_f32_e32 v7, v4
	v_lshl_add_u64 v[2:3], v[2:3], 0, s[90:91]
	v_lshlrev_b32_e32 v0, 1, v199
	v_lshl_add_u64 v[2:3], v[2:3], 0, v[0:1]
	s_mov_b64 s[0:1], 0x18628a00
	v_lshl_add_u64 v[2:3], v[2:3], 0, s[0:1]
	v_lshlrev_b32_e32 v0, 14, v198
	v_mul_f32_e32 v8, v64, v7
	v_lshl_add_u64 v[4:5], v[2:3], 0, v[0:1]
	v_cvt_pk_bf16_f32 v8, v8, v1
	flat_store_short v[4:5], v8
	v_mul_f32_e32 v8, v48, v7
	v_cvt_pk_bf16_f32 v8, v8, v1
	flat_store_short v[4:5], v8 offset:64
	v_mul_f32_e32 v8, v32, v7
	v_cvt_pk_bf16_f32 v8, v8, v1
	v_mul_f32_e32 v7, v16, v7
	flat_store_short v[4:5], v8 offset:128
	v_cvt_pk_bf16_f32 v7, v7, v1
	ds_read_b32 v8, v6 offset:4
	flat_store_short v[4:5], v7 offset:192
	v_or_b32_e32 v4, 0x1000, v0
	v_mov_b32_e32 v5, v1
	v_lshl_add_u64 v[4:5], v[2:3], 0, v[4:5]
	s_waitcnt lgkmcnt(0)
	v_rcp_f32_e32 v7, v8
	s_nop 0
	v_mul_f32_e32 v8, v65, v7
	v_cvt_pk_bf16_f32 v8, v8, v1
	flat_store_short v[4:5], v8
	v_mul_f32_e32 v8, v49, v7
	v_cvt_pk_bf16_f32 v8, v8, v1
	flat_store_short v[4:5], v8 offset:64
	v_mul_f32_e32 v8, v33, v7
	v_cvt_pk_bf16_f32 v8, v8, v1
	v_mul_f32_e32 v7, v17, v7
	flat_store_short v[4:5], v8 offset:128
	v_cvt_pk_bf16_f32 v7, v7, v1
	ds_read_b32 v8, v6 offset:8
	flat_store_short v[4:5], v7 offset:192
	v_or_b32_e32 v4, 0x2000, v0
	v_mov_b32_e32 v5, v1
	v_lshl_add_u64 v[4:5], v[2:3], 0, v[4:5]
	s_waitcnt lgkmcnt(0)
	v_rcp_f32_e32 v7, v8
	s_nop 0
	v_mul_f32_e32 v8, v66, v7
	v_cvt_pk_bf16_f32 v8, v8, v1
	flat_store_short v[4:5], v8
	v_mul_f32_e32 v8, v50, v7
	v_cvt_pk_bf16_f32 v8, v8, v1
	flat_store_short v[4:5], v8 offset:64
	v_mul_f32_e32 v8, v34, v7
	v_cvt_pk_bf16_f32 v8, v8, v1
	v_mul_f32_e32 v7, v18, v7
	flat_store_short v[4:5], v8 offset:128
	v_cvt_pk_bf16_f32 v7, v7, v1
	ds_read_b32 v8, v6 offset:12
	flat_store_short v[4:5], v7 offset:192
	v_or_b32_e32 v4, 0x3000, v0
	v_mov_b32_e32 v5, v1
	v_lshl_add_u64 v[4:5], v[2:3], 0, v[4:5]
	s_waitcnt lgkmcnt(0)
	v_rcp_f32_e32 v7, v8
	s_nop 0
	v_mul_f32_e32 v8, v67, v7
	v_cvt_pk_bf16_f32 v8, v8, v1
	flat_store_short v[4:5], v8
	v_mul_f32_e32 v8, v51, v7
	v_cvt_pk_bf16_f32 v8, v8, v1
	flat_store_short v[4:5], v8 offset:64
	v_mul_f32_e32 v8, v35, v7
	v_cvt_pk_bf16_f32 v8, v8, v1
	v_mul_f32_e32 v7, v19, v7
	flat_store_short v[4:5], v8 offset:128
	v_cvt_pk_bf16_f32 v7, v7, v1
	ds_read_b32 v8, v6 offset:32
	flat_store_short v[4:5], v7 offset:192
	v_or_b32_e32 v4, 0x8000, v0
	v_mov_b32_e32 v5, v1
	v_lshl_add_u64 v[4:5], v[2:3], 0, v[4:5]
	s_waitcnt lgkmcnt(0)
	v_rcp_f32_e32 v7, v8
	s_nop 0
	v_mul_f32_e32 v8, v68, v7
	v_cvt_pk_bf16_f32 v8, v8, v1
	flat_store_short v[4:5], v8
	v_mul_f32_e32 v8, v52, v7
	v_cvt_pk_bf16_f32 v8, v8, v1
	flat_store_short v[4:5], v8 offset:64
	v_mul_f32_e32 v8, v36, v7
	v_cvt_pk_bf16_f32 v8, v8, v1
	v_mul_f32_e32 v7, v20, v7
	flat_store_short v[4:5], v8 offset:128
	v_cvt_pk_bf16_f32 v7, v7, v1
	ds_read_b32 v8, v6 offset:36
	flat_store_short v[4:5], v7 offset:192
	v_or_b32_e32 v4, 0x9000, v0
	v_mov_b32_e32 v5, v1
	v_lshl_add_u64 v[4:5], v[2:3], 0, v[4:5]
	s_waitcnt lgkmcnt(0)
	v_rcp_f32_e32 v7, v8
	s_nop 0
	v_mul_f32_e32 v8, v69, v7
	v_cvt_pk_bf16_f32 v8, v8, v1
	flat_store_short v[4:5], v8
	v_mul_f32_e32 v8, v53, v7
	v_cvt_pk_bf16_f32 v8, v8, v1
	flat_store_short v[4:5], v8 offset:64
	v_mul_f32_e32 v8, v37, v7
	v_cvt_pk_bf16_f32 v8, v8, v1
	v_mul_f32_e32 v7, v21, v7
	flat_store_short v[4:5], v8 offset:128
	v_cvt_pk_bf16_f32 v7, v7, v1
	ds_read_b32 v8, v6 offset:40
	flat_store_short v[4:5], v7 offset:192
	v_or_b32_e32 v4, 0xa000, v0
	v_mov_b32_e32 v5, v1
	v_lshl_add_u64 v[4:5], v[2:3], 0, v[4:5]
	s_waitcnt lgkmcnt(0)
	v_rcp_f32_e32 v7, v8
	s_nop 0
	v_mul_f32_e32 v8, v70, v7
	v_cvt_pk_bf16_f32 v8, v8, v1
	flat_store_short v[4:5], v8
	v_mul_f32_e32 v8, v54, v7
	v_cvt_pk_bf16_f32 v8, v8, v1
	flat_store_short v[4:5], v8 offset:64
	v_mul_f32_e32 v8, v38, v7
	v_cvt_pk_bf16_f32 v8, v8, v1
	v_mul_f32_e32 v7, v22, v7
	flat_store_short v[4:5], v8 offset:128
	v_cvt_pk_bf16_f32 v7, v7, v1
	ds_read_b32 v8, v6 offset:44
	flat_store_short v[4:5], v7 offset:192
	v_or_b32_e32 v4, 0xb000, v0
	v_mov_b32_e32 v5, v1
	v_lshl_add_u64 v[4:5], v[2:3], 0, v[4:5]
	s_waitcnt lgkmcnt(0)
; __device__ __forceinline__ int crow(int r, int hi) { return (r & 3) + 8 * (r >> 2) + 4 * hi; }
; __device__ __forceinline__ unsigned cvtpk(float lo, float hi) { unsigned r; asm volatile("v_cvt_pk_bf16_f32 %0, %1, %2" : "=v"(r) : "v"(lo), "v"(hi)); return r; }
; template <int MODE>
; __device__ __forceinline__ void attn_unit(unsigned char* ws_, const float* rpb, const float* sink, int l, int h, int qb, int kvq, unsigned char* lds_g) {
;     ...
;   for (int r = 0; r < 16; ++r) { const int orow = crow(r, hi); const float rl = __builtin_amdgcn_rcpf(li_l[orow]);
; #pragma unroll
;     for (int d0 = 0; d0 < 4; ++d0) Ow[(size_t)orow * ldo + d0 * 32] = (bf16_t)(cvtpk(o[d0][r] * rl, 0.f) & 0xffffu); }
;   asm volatile("s_waitcnt lgkmcnt(0)" ::: "memory");
;   __syncthreads();
	v_rcp_f32_e32 v7, v8
	s_nop 0
	v_mul_f32_e32 v8, v71, v7
	v_cvt_pk_bf16_f32 v8, v8, v1
	flat_store_short v[4:5], v8
	v_mul_f32_e32 v8, v55, v7
	v_cvt_pk_bf16_f32 v8, v8, v1
	flat_store_short v[4:5], v8 offset:64
	v_mul_f32_e32 v8, v39, v7
	v_cvt_pk_bf16_f32 v8, v8, v1
	v_mul_f32_e32 v7, v23, v7
	flat_store_short v[4:5], v8 offset:128
	v_cvt_pk_bf16_f32 v7, v7, v1
	ds_read_b32 v8, v6 offset:64
	flat_store_short v[4:5], v7 offset:192
	v_or_b32_e32 v4, 0x10000, v0
	v_mov_b32_e32 v5, v1
	v_lshl_add_u64 v[4:5], v[2:3], 0, v[4:5]
	s_waitcnt lgkmcnt(0)
	v_rcp_f32_e32 v7, v8
	s_nop 0
	v_mul_f32_e32 v8, v72, v7
	v_cvt_pk_bf16_f32 v8, v8, v1
	flat_store_short v[4:5], v8
	v_mul_f32_e32 v8, v56, v7
	v_cvt_pk_bf16_f32 v8, v8, v1
	flat_store_short v[4:5], v8 offset:64
	v_mul_f32_e32 v8, v40, v7
	v_cvt_pk_bf16_f32 v8, v8, v1
	v_mul_f32_e32 v7, v24, v7
	flat_store_short v[4:5], v8 offset:128
	v_cvt_pk_bf16_f32 v7, v7, v1
	ds_read_b32 v8, v6 offset:68
	flat_store_short v[4:5], v7 offset:192
	v_or_b32_e32 v4, 0x11000, v0
	v_mov_b32_e32 v5, v1
	v_lshl_add_u64 v[4:5], v[2:3], 0, v[4:5]
	s_waitcnt lgkmcnt(0)
	v_rcp_f32_e32 v7, v8
	s_nop 0
	v_mul_f32_e32 v8, v73, v7
	v_cvt_pk_bf16_f32 v8, v8, v1
	flat_store_short v[4:5], v8
	v_mul_f32_e32 v8, v57, v7
	v_cvt_pk_bf16_f32 v8, v8, v1
	flat_store_short v[4:5], v8 offset:64
	v_mul_f32_e32 v8, v41, v7
	v_cvt_pk_bf16_f32 v8, v8, v1
	v_mul_f32_e32 v7, v25, v7
	flat_store_short v[4:5], v8 offset:128
	v_cvt_pk_bf16_f32 v7, v7, v1
	ds_read_b32 v8, v6 offset:72
	flat_store_short v[4:5], v7 offset:192
	v_or_b32_e32 v4, 0x12000, v0
	v_mov_b32_e32 v5, v1
	v_lshl_add_u64 v[4:5], v[2:3], 0, v[4:5]
	s_waitcnt lgkmcnt(0)
	v_rcp_f32_e32 v7, v8
	s_nop 0
	v_mul_f32_e32 v8, v74, v7
	v_cvt_pk_bf16_f32 v8, v8, v1
	flat_store_short v[4:5], v8
	v_mul_f32_e32 v8, v58, v7
	v_cvt_pk_bf16_f32 v8, v8, v1
	flat_store_short v[4:5], v8 offset:64
	v_mul_f32_e32 v8, v42, v7
	v_cvt_pk_bf16_f32 v8, v8, v1
	v_mul_f32_e32 v7, v26, v7
	flat_store_short v[4:5], v8 offset:128
	v_cvt_pk_bf16_f32 v7, v7, v1
	ds_read_b32 v8, v6 offset:76
	flat_store_short v[4:5], v7 offset:192
	v_or_b32_e32 v4, 0x13000, v0
	v_mov_b32_e32 v5, v1
	v_lshl_add_u64 v[4:5], v[2:3], 0, v[4:5]
	s_waitcnt lgkmcnt(0)
	v_rcp_f32_e32 v7, v8
	s_nop 0
	v_mul_f32_e32 v8, v75, v7
	v_cvt_pk_bf16_f32 v8, v8, v1
	flat_store_short v[4:5], v8
	v_mul_f32_e32 v8, v59, v7
	v_cvt_pk_bf16_f32 v8, v8, v1
	flat_store_short v[4:5], v8 offset:64
	v_mul_f32_e32 v8, v43, v7
	v_cvt_pk_bf16_f32 v8, v8, v1
	v_mul_f32_e32 v7, v27, v7
	flat_store_short v[4:5], v8 offset:128
	v_cvt_pk_bf16_f32 v7, v7, v1
	ds_read_b32 v8, v6 offset:96
	flat_store_short v[4:5], v7 offset:192
	v_or_b32_e32 v4, 0x18000, v0
	v_mov_b32_e32 v5, v1
	v_lshl_add_u64 v[4:5], v[2:3], 0, v[4:5]
	s_waitcnt lgkmcnt(0)
	v_rcp_f32_e32 v7, v8
	s_nop 0
	v_mul_f32_e32 v8, v76, v7
	v_cvt_pk_bf16_f32 v8, v8, v1
	flat_store_short v[4:5], v8
	v_mul_f32_e32 v8, v60, v7
	v_cvt_pk_bf16_f32 v8, v8, v1
	flat_store_short v[4:5], v8 offset:64
	v_mul_f32_e32 v8, v44, v7
	v_cvt_pk_bf16_f32 v8, v8, v1
	v_mul_f32_e32 v7, v28, v7
	flat_store_short v[4:5], v8 offset:128
	v_cvt_pk_bf16_f32 v7, v7, v1
	ds_read_b32 v8, v6 offset:100
	flat_store_short v[4:5], v7 offset:192
	v_or_b32_e32 v4, 0x19000, v0
	v_mov_b32_e32 v5, v1
	v_lshl_add_u64 v[4:5], v[2:3], 0, v[4:5]
	s_waitcnt lgkmcnt(0)
	v_rcp_f32_e32 v7, v8
	s_nop 0
	v_mul_f32_e32 v8, v77, v7
	v_cvt_pk_bf16_f32 v8, v8, v1
	flat_store_short v[4:5], v8
	v_mul_f32_e32 v8, v61, v7
	v_cvt_pk_bf16_f32 v8, v8, v1
	flat_store_short v[4:5], v8 offset:64
	v_mul_f32_e32 v8, v45, v7
	v_cvt_pk_bf16_f32 v8, v8, v1
	v_mul_f32_e32 v7, v29, v7
	flat_store_short v[4:5], v8 offset:128
	v_cvt_pk_bf16_f32 v7, v7, v1
	ds_read_b32 v8, v6 offset:104
	flat_store_short v[4:5], v7 offset:192
	v_or_b32_e32 v4, 0x1a000, v0
	v_mov_b32_e32 v5, v1
	v_lshl_add_u64 v[4:5], v[2:3], 0, v[4:5]
	s_waitcnt lgkmcnt(0)
	v_rcp_f32_e32 v7, v8
	v_or_b32_e32 v0, 0x1b000, v0
	v_lshl_add_u64 v[2:3], v[2:3], 0, v[0:1]
	v_mul_f32_e32 v8, v78, v7
	v_cvt_pk_bf16_f32 v8, v8, v1
	flat_store_short v[4:5], v8
	v_mul_f32_e32 v8, v62, v7
	v_cvt_pk_bf16_f32 v8, v8, v1
	flat_store_short v[4:5], v8 offset:64
	v_mul_f32_e32 v8, v46, v7
	v_mul_f32_e32 v7, v30, v7
	v_cvt_pk_bf16_f32 v8, v8, v1
	flat_store_short v[4:5], v8 offset:128
	v_cvt_pk_bf16_f32 v7, v7, v1
	ds_read_b32 v6, v6 offset:108
	flat_store_short v[4:5], v7 offset:192
	s_waitcnt lgkmcnt(0)
	v_rcp_f32_e32 v6, v6
	s_nop 0
	v_mul_f32_e32 v0, v79, v6
	v_cvt_pk_bf16_f32 v0, v0, v1
	flat_store_short v[2:3], v0
	v_mul_f32_e32 v0, v63, v6
	v_cvt_pk_bf16_f32 v0, v0, v1
	flat_store_short v[2:3], v0 offset:64
	v_mul_f32_e32 v0, v47, v6
	v_cvt_pk_bf16_f32 v0, v0, v1
	flat_store_short v[2:3], v0 offset:128
	v_mul_f32_e32 v0, v31, v6
	v_cvt_pk_bf16_f32 v0, v0, v1
	flat_store_short v[2:3], v0 offset:192
	s_waitcnt lgkmcnt(0)
	s_barrier

; __device__ __forceinline__ int crow(int r, int hi) { return (r & 3) + 8 * (r >> 2) + 4 * hi; }
; __device__ __forceinline__ unsigned cvtpk(float lo, float hi) { unsigned r; asm volatile("v_cvt_pk_bf16_f32 %0, %1, %2" : "=v"(r) : "v"(lo), "v"(hi)); return r; }
; template <int MODE>
; __device__ __forceinline__ void attn_unit(unsigned char* ws_, const float* rpb, const float* sink, int l, int h, int qb, int kvq, unsigned char* lds_g) {
;     ...
;   if (hi == 0) li_l[r32] = l_reg; asm volatile("s_waitcnt lgkmcnt(0)" ::: "memory");
;   bf16_t* Ow; int ldo;
;   if (MODE == 1) { Ow = (bf16_t*)(ws_ + WS_PART) + ((size_t)kvq * S + q0 + wid * 32) * VLD + 128 * h + r32; ldo = VLD;
;     if (hi == 0) { float* st = (float*)(ws_ + WS_STAT) + ((size_t)(kvq * 6 + h) * S + qi) * 2; st[0] = m_reg; st[1] = l_reg; } }
;   else { Ow = (bf16_t*)(ws_ + WS_Y) + (size_t)(q0 + wid * 32) * DM + ycol + r32; ldo = DM; }
; #pragma unroll
;   for (int r = 0; r < 16; ++r) { const int orow = crow(r, hi); const float rl = __builtin_amdgcn_rcpf(li_l[orow]);
; #pragma unroll
;     for (int d0 = 0; d0 < 4; ++d0) Ow[(size_t)orow * ldo + d0 * 32] = (bf16_t)(cvtpk(o[d0][r] * rl, 0.f) & 0xffffu); }
.LBB0_859:
	s_or_b64 exec, exec, s[8:9]
	s_lshl_b32 s4, s14, 13
	s_or_b32 s4, s4, s16
	v_add_u32_e32 v0, s4, v179
	v_mov_b64_e32 v[66:67], s[2:3]
	v_mad_i64_i32 v[66:67], s[2:3], v0, s33, v[66:67]
	v_lshl_add_u64 v[66:67], s[6:7], 1, v[66:67]
	v_lshlrev_b32_e32 v0, 1, v177
	v_lshl_add_u32 v70, v176, 4, v178
	v_lshl_add_u64 v[66:67], v[66:67], 0, v[0:1]
	ds_read_b32 v0, v70
	s_mov_b64 s[2:3], 0x1fe28000
	v_lshl_add_u64 v[66:67], v[66:67], 0, s[2:3]
	s_add_i32 s13, s13, s12
	s_cmpk_gt_i32 s13, 0x2ff
	s_waitcnt lgkmcnt(0)
	v_rcp_f32_e32 v71, v0
	v_mul_u32_u24_e32 v0, 0x1800, v176
	v_lshl_add_u64 v[68:69], v[66:67], 0, v[0:1]
	v_mul_f32_e32 v0, v2, v71
	v_cvt_pk_bf16_f32 v0, v0, v1
	flat_store_short v[68:69], v0
	v_mul_f32_e32 v0, v50, v71
	v_cvt_pk_bf16_f32 v0, v0, v1
	flat_store_short v[68:69], v0 offset:64
	v_mul_f32_e32 v0, v34, v71
	v_cvt_pk_bf16_f32 v0, v0, v1
	flat_store_short v[68:69], v0 offset:128
	v_mul_f32_e32 v0, v18, v71
	v_cvt_pk_bf16_f32 v0, v0, v1
	flat_store_short v[68:69], v0 offset:192
	ds_read_b32 v0, v70 offset:4
	v_lshl_or_b32 v18, v176, 2, 1
	s_waitcnt lgkmcnt(0)
	v_rcp_f32_e32 v2, v0
	v_mul_u32_u24_e32 v0, 0x600, v18
	v_lshl_add_u64 v[68:69], v[66:67], 0, v[0:1]
	v_mul_f32_e32 v0, v3, v2
	v_cvt_pk_bf16_f32 v0, v0, v1
	flat_store_short v[68:69], v0
	v_mul_f32_e32 v0, v51, v2
	v_cvt_pk_bf16_f32 v0, v0, v1
	flat_store_short v[68:69], v0 offset:64
	v_mul_f32_e32 v0, v35, v2
	v_cvt_pk_bf16_f32 v0, v0, v1
	flat_store_short v[68:69], v0 offset:128
	v_mul_f32_e32 v0, v19, v2
	v_cvt_pk_bf16_f32 v0, v0, v1
	flat_store_short v[68:69], v0 offset:192
	ds_read_b32 v0, v70 offset:8
	s_waitcnt lgkmcnt(0)
	v_rcp_f32_e32 v19, v0
	v_mad_u32_u24 v0, v18, s33, s33
	v_lshl_add_u64 v[2:3], v[66:67], 0, v[0:1]
	v_mul_f32_e32 v0, v4, v19
	v_cvt_pk_bf16_f32 v0, v0, v1
	flat_store_short v[2:3], v0
	v_mul_f32_e32 v0, v52, v19
	v_cvt_pk_bf16_f32 v0, v0, v1
	flat_store_short v[2:3], v0 offset:64
	v_mul_f32_e32 v0, v36, v19
	v_cvt_pk_bf16_f32 v0, v0, v1
	flat_store_short v[2:3], v0 offset:128
	v_mul_f32_e32 v0, v20, v19
	v_cvt_pk_bf16_f32 v0, v0, v1
	flat_store_short v[2:3], v0 offset:192
	ds_read_b32 v0, v70 offset:12
	s_waitcnt lgkmcnt(0)
	v_rcp_f32_e32 v4, v0
	v_mov_b32_e32 v0, 0xc00
	v_mad_u32_u24 v0, v18, s33, v0
	v_lshl_add_u64 v[2:3], v[66:67], 0, v[0:1]
	v_mul_f32_e32 v0, v5, v4
	v_cvt_pk_bf16_f32 v0, v0, v1
	flat_store_short v[2:3], v0
	v_mul_f32_e32 v0, v53, v4
	v_cvt_pk_bf16_f32 v0, v0, v1
	flat_store_short v[2:3], v0 offset:64
	v_mul_f32_e32 v0, v37, v4
	v_cvt_pk_bf16_f32 v0, v0, v1
	flat_store_short v[2:3], v0 offset:128
	v_mul_f32_e32 v0, v21, v4
	v_cvt_pk_bf16_f32 v0, v0, v1
	flat_store_short v[2:3], v0 offset:192
	ds_read_b32 v0, v70 offset:32
	s_waitcnt lgkmcnt(0)
	v_rcp_f32_e32 v4, v0
	v_mov_b32_e32 v0, 0x2a00
	v_mad_u32_u24 v0, v18, s33, v0
	v_lshl_add_u64 v[2:3], v[66:67], 0, v[0:1]
	v_mul_f32_e32 v0, v6, v4
	v_cvt_pk_bf16_f32 v0, v0, v1
	flat_store_short v[2:3], v0
	v_mul_f32_e32 v0, v54, v4
	v_cvt_pk_bf16_f32 v0, v0, v1
	flat_store_short v[2:3], v0 offset:64
	v_mul_f32_e32 v0, v38, v4
	v_cvt_pk_bf16_f32 v0, v0, v1
	flat_store_short v[2:3], v0 offset:128
	v_mul_f32_e32 v0, v22, v4
	v_cvt_pk_bf16_f32 v0, v0, v1
	flat_store_short v[2:3], v0 offset:192
	ds_read_b32 v0, v70 offset:36
	s_waitcnt lgkmcnt(0)
	v_rcp_f32_e32 v4, v0
	v_mov_b32_e32 v0, 0x3000
	v_mad_u32_u24 v0, v18, s33, v0
	v_lshl_add_u64 v[2:3], v[66:67], 0, v[0:1]
	v_mul_f32_e32 v0, v7, v4
	v_cvt_pk_bf16_f32 v0, v0, v1
	flat_store_short v[2:3], v0
	v_mul_f32_e32 v0, v55, v4
	v_cvt_pk_bf16_f32 v0, v0, v1
	flat_store_short v[2:3], v0 offset:64
	v_mul_f32_e32 v0, v39, v4
	v_cvt_pk_bf16_f32 v0, v0, v1
	flat_store_short v[2:3], v0 offset:128
	v_mul_f32_e32 v0, v23, v4
	v_cvt_pk_bf16_f32 v0, v0, v1
	flat_store_short v[2:3], v0 offset:192
	ds_read_b32 v0, v70 offset:40
	s_waitcnt lgkmcnt(0)
	v_rcp_f32_e32 v4, v0
	v_mov_b32_e32 v0, 0x3600
	v_mad_u32_u24 v0, v18, s33, v0
	v_lshl_add_u64 v[2:3], v[66:67], 0, v[0:1]
	v_mul_f32_e32 v0, v8, v4
	v_cvt_pk_bf16_f32 v0, v0, v1
	flat_store_short v[2:3], v0
	v_mul_f32_e32 v0, v56, v4
	v_cvt_pk_bf16_f32 v0, v0, v1
	flat_store_short v[2:3], v0 offset:64
	v_mul_f32_e32 v0, v40, v4
	v_cvt_pk_bf16_f32 v0, v0, v1
	flat_store_short v[2:3], v0 offset:128
	v_mul_f32_e32 v0, v24, v4
	v_cvt_pk_bf16_f32 v0, v0, v1
	flat_store_short v[2:3], v0 offset:192
	ds_read_b32 v0, v70 offset:44
	s_waitcnt lgkmcnt(0)
; __device__ __forceinline__ int crow(int r, int hi) { return (r & 3) + 8 * (r >> 2) + 4 * hi; }
; __device__ __forceinline__ unsigned cvtpk(float lo, float hi) { unsigned r; asm volatile("v_cvt_pk_bf16_f32 %0, %1, %2" : "=v"(r) : "v"(lo), "v"(hi)); return r; }
; template <int MODE>
; __device__ __forceinline__ void attn_unit(unsigned char* ws_, const float* rpb, const float* sink, int l, int h, int qb, int kvq, unsigned char* lds_g) {
;     ...
;   for (int r = 0; r < 16; ++r) { const int orow = crow(r, hi); const float rl = __builtin_amdgcn_rcpf(li_l[orow]);
; #pragma unroll
;     for (int d0 = 0; d0 < 4; ++d0) Ow[(size_t)orow * ldo + d0 * 32] = (bf16_t)(cvtpk(o[d0][r] * rl, 0.f) & 0xffffu); }
;   asm volatile("s_waitcnt lgkmcnt(0)" ::: "memory");
;   __syncthreads();
	v_rcp_f32_e32 v4, v0
	v_mov_b32_e32 v0, 0x3c00
	v_mad_u32_u24 v0, v18, s33, v0
	v_lshl_add_u64 v[2:3], v[66:67], 0, v[0:1]
	v_mul_f32_e32 v0, v9, v4
	v_cvt_pk_bf16_f32 v0, v0, v1
	flat_store_short v[2:3], v0
	v_mul_f32_e32 v0, v57, v4
	v_cvt_pk_bf16_f32 v0, v0, v1
	flat_store_short v[2:3], v0 offset:64
	v_mul_f32_e32 v0, v41, v4
	v_cvt_pk_bf16_f32 v0, v0, v1
	flat_store_short v[2:3], v0 offset:128
	v_mul_f32_e32 v0, v25, v4
	v_cvt_pk_bf16_f32 v0, v0, v1
	flat_store_short v[2:3], v0 offset:192
	ds_read_b32 v0, v70 offset:64
	s_waitcnt lgkmcnt(0)
	v_rcp_f32_e32 v4, v0
	v_mov_b32_e32 v0, 0x5a00
	v_mad_u32_u24 v0, v18, s33, v0
	v_lshl_add_u64 v[2:3], v[66:67], 0, v[0:1]
	v_mul_f32_e32 v0, v10, v4
	v_cvt_pk_bf16_f32 v0, v0, v1
	flat_store_short v[2:3], v0
	v_mul_f32_e32 v0, v58, v4
	v_cvt_pk_bf16_f32 v0, v0, v1
	flat_store_short v[2:3], v0 offset:64
	v_mul_f32_e32 v0, v42, v4
	v_cvt_pk_bf16_f32 v0, v0, v1
	flat_store_short v[2:3], v0 offset:128
	v_mul_f32_e32 v0, v26, v4
	v_cvt_pk_bf16_f32 v0, v0, v1
	flat_store_short v[2:3], v0 offset:192
	ds_read_b32 v0, v70 offset:68
	s_waitcnt lgkmcnt(0)
	v_rcp_f32_e32 v4, v0
	v_mad_u32_u24 v0, v18, s33, v223
	v_lshl_add_u64 v[2:3], v[66:67], 0, v[0:1]
	v_mul_f32_e32 v0, v11, v4
	v_cvt_pk_bf16_f32 v0, v0, v1
	flat_store_short v[2:3], v0
	v_mul_f32_e32 v0, v59, v4
	v_cvt_pk_bf16_f32 v0, v0, v1
	flat_store_short v[2:3], v0 offset:64
	v_mul_f32_e32 v0, v43, v4
	v_cvt_pk_bf16_f32 v0, v0, v1
	flat_store_short v[2:3], v0 offset:128
	v_mul_f32_e32 v0, v27, v4
	v_cvt_pk_bf16_f32 v0, v0, v1
	flat_store_short v[2:3], v0 offset:192
	ds_read_b32 v0, v70 offset:72
	s_waitcnt lgkmcnt(0)
	v_rcp_f32_e32 v4, v0
	v_mad_u32_u24 v0, v18, s33, v224
	v_lshl_add_u64 v[2:3], v[66:67], 0, v[0:1]
	v_mul_f32_e32 v0, v12, v4
	v_cvt_pk_bf16_f32 v0, v0, v1
	flat_store_short v[2:3], v0
	v_mul_f32_e32 v0, v60, v4
	v_cvt_pk_bf16_f32 v0, v0, v1
	flat_store_short v[2:3], v0 offset:64
	v_mul_f32_e32 v0, v44, v4
	v_cvt_pk_bf16_f32 v0, v0, v1
	flat_store_short v[2:3], v0 offset:128
	v_mul_f32_e32 v0, v28, v4
	v_cvt_pk_bf16_f32 v0, v0, v1
	flat_store_short v[2:3], v0 offset:192
	ds_read_b32 v0, v70 offset:76
	s_waitcnt lgkmcnt(0)
	v_rcp_f32_e32 v4, v0
	v_mad_u32_u24 v0, v18, s33, v225
	v_lshl_add_u64 v[2:3], v[66:67], 0, v[0:1]
	v_mul_f32_e32 v0, v13, v4
	v_cvt_pk_bf16_f32 v0, v0, v1
	flat_store_short v[2:3], v0
	v_mul_f32_e32 v0, v61, v4
	v_cvt_pk_bf16_f32 v0, v0, v1
	flat_store_short v[2:3], v0 offset:64
	v_mul_f32_e32 v0, v45, v4
	v_cvt_pk_bf16_f32 v0, v0, v1
	flat_store_short v[2:3], v0 offset:128
	v_mul_f32_e32 v0, v29, v4
	v_cvt_pk_bf16_f32 v0, v0, v1
	flat_store_short v[2:3], v0 offset:192
	ds_read_b32 v0, v70 offset:96
	s_waitcnt lgkmcnt(0)
	v_rcp_f32_e32 v4, v0
	v_mad_u32_u24 v0, v18, s33, v226
	v_lshl_add_u64 v[2:3], v[66:67], 0, v[0:1]
	v_mul_f32_e32 v0, v14, v4
	v_cvt_pk_bf16_f32 v0, v0, v1
	flat_store_short v[2:3], v0
	v_mul_f32_e32 v0, v62, v4
	v_cvt_pk_bf16_f32 v0, v0, v1
	flat_store_short v[2:3], v0 offset:64
	v_mul_f32_e32 v0, v46, v4
	v_cvt_pk_bf16_f32 v0, v0, v1
	flat_store_short v[2:3], v0 offset:128
	v_mul_f32_e32 v0, v30, v4
	v_cvt_pk_bf16_f32 v0, v0, v1
	flat_store_short v[2:3], v0 offset:192
	ds_read_b32 v0, v70 offset:100
	s_waitcnt lgkmcnt(0)
	v_rcp_f32_e32 v4, v0
	v_mad_u32_u24 v0, v18, s33, v227
	v_lshl_add_u64 v[2:3], v[66:67], 0, v[0:1]
	v_mul_f32_e32 v0, v15, v4
	v_cvt_pk_bf16_f32 v0, v0, v1
	flat_store_short v[2:3], v0
	v_mul_f32_e32 v0, v63, v4
	v_cvt_pk_bf16_f32 v0, v0, v1
	flat_store_short v[2:3], v0 offset:64
	v_mul_f32_e32 v0, v47, v4
	v_cvt_pk_bf16_f32 v0, v0, v1
	flat_store_short v[2:3], v0 offset:128
	v_mul_f32_e32 v0, v31, v4
	v_cvt_pk_bf16_f32 v0, v0, v1
	flat_store_short v[2:3], v0 offset:192
	ds_read_b32 v0, v70 offset:104
	s_waitcnt lgkmcnt(0)
	v_rcp_f32_e32 v4, v0
	v_mad_u32_u24 v0, v18, s33, v228
	v_lshl_add_u64 v[2:3], v[66:67], 0, v[0:1]
	v_mul_f32_e32 v0, v16, v4
	v_cvt_pk_bf16_f32 v0, v0, v1
	flat_store_short v[2:3], v0
	v_mul_f32_e32 v0, v64, v4
	v_cvt_pk_bf16_f32 v0, v0, v1
	flat_store_short v[2:3], v0 offset:64
	v_mul_f32_e32 v0, v48, v4
	v_cvt_pk_bf16_f32 v0, v0, v1
	flat_store_short v[2:3], v0 offset:128
	v_mul_f32_e32 v0, v32, v4
	v_cvt_pk_bf16_f32 v0, v0, v1
	flat_store_short v[2:3], v0 offset:192
	ds_read_b32 v0, v70 offset:108
	s_waitcnt lgkmcnt(0)
	v_rcp_f32_e32 v4, v0
	v_mad_u32_u24 v0, v18, s33, v229
	v_lshl_add_u64 v[2:3], v[66:67], 0, v[0:1]
	v_mul_f32_e32 v0, v17, v4
	v_cvt_pk_bf16_f32 v0, v0, v1
	flat_store_short v[2:3], v0
	v_mul_f32_e32 v0, v65, v4
	v_cvt_pk_bf16_f32 v0, v0, v1
	flat_store_short v[2:3], v0 offset:64
	v_mul_f32_e32 v0, v49, v4
	v_cvt_pk_bf16_f32 v0, v0, v1
	flat_store_short v[2:3], v0 offset:128
	v_mul_f32_e32 v0, v33, v4
	v_cvt_pk_bf16_f32 v0, v0, v1
	flat_store_short v[2:3], v0 offset:192
	s_waitcnt lgkmcnt(0)
	s_barrier
	s_cbranch_scc1 .LBB0_882
